# grid barrier spin loops poll without s_sleep (faster release detection)
# baseline (speedup 1.0000x reference)
.LBB0_302:
	v_readlane_b32 s8, v252, 36
	v_readlane_b32 s9, v252, 37
	v_readlane_b32 s5, v254, 61
	s_mov_b64 s[10:11], -1
	s_nop 2
	global_load_dword v0, v1, s[8:9] sc1
	v_readlane_b32 s8, v252, 38
	v_readlane_b32 s9, v252, 39
	s_waitcnt lgkmcnt(0)
	s_nop 3
	global_load_dword v2, v1, s[8:9] sc1
	v_readlane_b32 s8, v252, 40
	v_readlane_b32 s9, v252, 41
	s_waitcnt vmcnt(0)
	v_add_u32_e32 v17, v2, v0
	s_nop 2
	global_load_dword v3, v1, s[8:9] sc1
	v_readlane_b32 s8, v252, 42
	v_readlane_b32 s9, v252, 43
	s_waitcnt vmcnt(0)
	v_add_u32_e32 v17, v17, v3
	s_nop 2
	global_load_dword v4, v1, s[8:9] sc1
	v_readlane_b32 s8, v252, 44
	v_readlane_b32 s9, v252, 45
	s_waitcnt vmcnt(0)
	v_add_u32_e32 v17, v17, v4
	s_nop 2
	global_load_dword v5, v1, s[8:9] sc1
	v_readlane_b32 s8, v252, 46
	v_readlane_b32 s9, v252, 47
	s_waitcnt vmcnt(0)
	v_add_u32_e32 v17, v17, v5
	s_nop 2
	global_load_dword v6, v1, s[8:9] sc1
	v_readlane_b32 s8, v252, 48
	v_readlane_b32 s9, v252, 49
	s_waitcnt vmcnt(0)
	v_add_u32_e32 v17, v17, v6
	s_nop 2
	global_load_dword v7, v1, s[8:9] sc1
	v_readlane_b32 s8, v252, 50
	v_readlane_b32 s9, v252, 51
	s_waitcnt vmcnt(0)
	v_add_u32_e32 v17, v17, v7
	s_nop 2
	global_load_dword v8, v1, s[8:9] sc1
	v_readlane_b32 s8, v252, 52
	v_readlane_b32 s9, v252, 53
	s_waitcnt vmcnt(0)
	v_add_u32_e32 v17, v17, v8
	s_nop 2
	global_load_dword v9, v1, s[8:9] sc1
	v_readlane_b32 s8, v252, 54
	v_readlane_b32 s9, v252, 55
	s_waitcnt vmcnt(0)
	v_add_u32_e32 v17, v17, v9
	s_nop 2
	global_load_dword v10, v1, s[8:9] sc1
	v_readlane_b32 s8, v252, 56
	v_readlane_b32 s9, v252, 57
	s_waitcnt vmcnt(0)
	v_add_u32_e32 v17, v17, v10
	s_nop 2
	global_load_dword v11, v1, s[8:9] sc1
	v_readlane_b32 s8, v252, 58
	v_readlane_b32 s9, v252, 59
	s_waitcnt vmcnt(0)
	v_add_u32_e32 v17, v17, v11
	s_nop 2
	global_load_dword v12, v1, s[8:9] sc1
	v_readlane_b32 s8, v252, 60
	v_readlane_b32 s9, v252, 61
	s_waitcnt vmcnt(0)
	v_add_u32_e32 v17, v17, v12
	s_nop 2
	global_load_dword v13, v1, s[8:9] sc1
	v_readlane_b32 s8, v252, 62
	v_readlane_b32 s9, v252, 63
	s_waitcnt vmcnt(0)
	v_add_u32_e32 v17, v17, v13
	s_nop 2
	global_load_dword v14, v1, s[8:9] sc1
	v_readlane_b32 s8, v253, 0
	v_readlane_b32 s9, v253, 1
	s_waitcnt vmcnt(0)
	v_add_u32_e32 v17, v17, v14
	s_nop 2
	global_load_dword v15, v1, s[8:9] sc1
	v_readlane_b32 s8, v253, 2
	v_readlane_b32 s9, v253, 3
	s_waitcnt vmcnt(0)
	v_add_u32_e32 v17, v17, v15
	s_nop 2
	global_load_dword v16, v1, s[8:9] sc1
	s_mov_b64 s[8:9], -1
	s_waitcnt vmcnt(0)
	v_add_u32_e32 v17, v17, v16
	v_cmp_eq_u32_e32 vcc, s5, v17
	s_cbranch_vccnz .LBB0_301
	s_and_b32 s5, s4, 0xff
	s_cmp_eq_u32 s5, 0
	s_mov_b64 s[12:13], -1
	s_nop 0
	s_cbranch_scc1 .LBB0_306
	s_and_b64 vcc, exec, s[12:13]
	s_cbranch_vccz .LBB0_301

.LBB0_318:
	s_and_b32 s5, s4, 0xff
	s_mov_b64 s[16:17], -1
	s_cmp_lg_u32 s5, 0
	s_mov_b64 s[40:41], -1
	s_nop 0
	s_cbranch_scc0 .LBB0_321
	s_and_b64 vcc, exec, s[40:41]
	s_cbranch_vccz .LBB0_317

.LBB0_1142:
	v_readlane_b32 s4, v252, 36
	v_readlane_b32 s5, v252, 37
	s_mov_b64 s[8:9], -1
	s_mov_b64 s[10:11], -1
	s_nop 2
	global_load_dword v0, v1, s[4:5] sc1
	v_readlane_b32 s4, v252, 38
	v_readlane_b32 s5, v252, 39
	s_waitcnt lgkmcnt(0)
	s_nop 3
	global_load_dword v2, v1, s[4:5] sc1
	v_readlane_b32 s4, v252, 40
	v_readlane_b32 s5, v252, 41
	s_waitcnt vmcnt(0)
	v_add_u32_e32 v17, v2, v0
	s_nop 2
	global_load_dword v3, v1, s[4:5] sc1
	v_readlane_b32 s4, v252, 42
	v_readlane_b32 s5, v252, 43
	s_waitcnt vmcnt(0)
	v_add_u32_e32 v17, v17, v3
	s_nop 2
	global_load_dword v4, v1, s[4:5] sc1
	v_readlane_b32 s4, v252, 44
	v_readlane_b32 s5, v252, 45
	s_waitcnt vmcnt(0)
	v_add_u32_e32 v17, v17, v4
	s_nop 2
	global_load_dword v5, v1, s[4:5] sc1
	v_readlane_b32 s4, v252, 46
	v_readlane_b32 s5, v252, 47
	s_waitcnt vmcnt(0)
	v_add_u32_e32 v17, v17, v5
	s_nop 2
	global_load_dword v6, v1, s[4:5] sc1
	v_readlane_b32 s4, v252, 48
	v_readlane_b32 s5, v252, 49
	s_waitcnt vmcnt(0)
	v_add_u32_e32 v17, v17, v6
	s_nop 2
	global_load_dword v7, v1, s[4:5] sc1
	v_readlane_b32 s4, v252, 50
	v_readlane_b32 s5, v252, 51
	s_waitcnt vmcnt(0)
	v_add_u32_e32 v17, v17, v7
	s_nop 2
	global_load_dword v8, v1, s[4:5] sc1
	v_readlane_b32 s4, v252, 52
	v_readlane_b32 s5, v252, 53
	s_waitcnt vmcnt(0)
	v_add_u32_e32 v17, v17, v8
	s_nop 2
	global_load_dword v9, v1, s[4:5] sc1
	v_readlane_b32 s4, v252, 54
	v_readlane_b32 s5, v252, 55
	s_waitcnt vmcnt(0)
	v_add_u32_e32 v17, v17, v9
	s_nop 2
	global_load_dword v10, v1, s[4:5] sc1
	v_readlane_b32 s4, v252, 56
	v_readlane_b32 s5, v252, 57
	s_waitcnt vmcnt(0)
	v_add_u32_e32 v17, v17, v10
	s_nop 2
	global_load_dword v11, v1, s[4:5] sc1
	v_readlane_b32 s4, v252, 58
	v_readlane_b32 s5, v252, 59
	s_waitcnt vmcnt(0)
	v_add_u32_e32 v17, v17, v11
	s_nop 2
	global_load_dword v12, v1, s[4:5] sc1
	v_readlane_b32 s4, v252, 60
	v_readlane_b32 s5, v252, 61
	s_waitcnt vmcnt(0)
	v_add_u32_e32 v17, v17, v12
	s_nop 2
	global_load_dword v13, v1, s[4:5] sc1
	v_readlane_b32 s4, v252, 62
	v_readlane_b32 s5, v252, 63
	s_waitcnt vmcnt(0)
	v_add_u32_e32 v17, v17, v13
	s_nop 2
	global_load_dword v14, v1, s[4:5] sc1
	v_readlane_b32 s4, v253, 0
	v_readlane_b32 s5, v253, 1
	s_waitcnt vmcnt(0)
	v_add_u32_e32 v17, v17, v14
	s_nop 2
	global_load_dword v15, v1, s[4:5] sc1
	v_readlane_b32 s4, v253, 2
	v_readlane_b32 s5, v253, 3
	s_waitcnt vmcnt(0)
	v_add_u32_e32 v17, v17, v15
	s_nop 2
	global_load_dword v16, v1, s[4:5] sc1
	v_readlane_b32 s4, v254, 61
	s_waitcnt vmcnt(0)
	v_add_u32_e32 v17, v17, v16
	v_cmp_eq_u32_e32 vcc, s4, v17
	s_cbranch_vccnz .LBB0_1141
	s_and_b32 s4, s1, 0xff
	s_cmp_eq_u32 s4, 0
	s_mov_b64 s[12:13], -1
	s_nop 0
	s_cbranch_scc1 .LBB0_1146
	s_and_b64 vcc, exec, s[12:13]
	s_cbranch_vccz .LBB0_1141

.LBB0_1158:
	s_and_b32 s4, s1, 0xff
	s_mov_b64 s[16:17], -1
	s_cmp_lg_u32 s4, 0
	s_mov_b64 s[38:39], -1
	s_nop 0
	s_cbranch_scc0 .LBB0_1161
	s_and_b64 vcc, exec, s[38:39]
	s_cbranch_vccz .LBB0_1157
